# grid barrier: the middle arriver of each XCD (rank 16) fires one extra asynchronous L2 write-back so the last arriver's blocking flush is shorter; on top of nt4
# baseline (speedup 1.0000x reference)
; __device__ __forceinline__ unsigned xb_ld(unsigned* p)              { return __hip_atomic_load(p, __ATOMIC_RELAXED, __HIP_MEMORY_SCOPE_AGENT); }
; __device__ __forceinline__ unsigned xb_add(unsigned* p, unsigned v) { return __hip_atomic_fetch_add(p, v, __ATOMIC_RELAXED, __HIP_MEMORY_SCOPE_AGENT); }
; #define XB_SPIN(cond, bar) do { unsigned _sp = 0; while (cond) { __builtin_amdgcn_s_sleep(1); \
;     if ((++_sp & 255u) == 0u) { if (xb_ld(&(bar)[XB_TMO])) break; if (_sp > XB_SPIN_CAP) { atomicAdd(&(bar)[XB_TMO], 1u); break; } } } } while (0)
; __device__ __forceinline__ void xcd_barrier(const XcdBarrier& b) {
;     ...
;         const unsigned old = xb_add(&bar[XB_XSUB(b.x)], 1u);
;         const unsigned gen = old / nloc;
;         if (old + 1u == (gen + 1u) * nloc) {
;             __builtin_amdgcn_fence(__ATOMIC_RELEASE, "agent");
;             asm volatile("s_waitcnt vmcnt(0)" ::: "memory");
;             const unsigned og = xb_add(&bar[XB_TOP], 1u);
;             const unsigned tg = og / nx;
;             if (og + 1u == (tg + 1u) * nx) xb_add(&bar[XB_TOPGEN], 1u);
;             else XB_SPIN(xb_ld(&bar[XB_TOPGEN]) == tg, bar);
;             __builtin_amdgcn_fence(__ATOMIC_ACQUIRE, "agent");
;             asm volatile("s_waitcnt vmcnt(0)" ::: "memory");
;         } else {
;             XB_SPIN(xb_ld(&bar[XB_TOPGEN]) == gen, bar);
;             __builtin_amdgcn_fence(__ATOMIC_ACQUIRE, "agent");
;             asm volatile("s_waitcnt vmcnt(0)" ::: "memory");
.LBB0_214:
	s_or_b64 exec, exec, s[6:7]
	v_cvt_f32_u32_e32 v4, v2
	s_waitcnt vmcnt(0)
	v_readfirstlane_b32 s6, v3
	v_sub_u32_e32 v3, 0, v2
	v_rcp_iflag_f32_e32 v4, v4
	v_add_u32_e32 v5, s6, v1
	v_mul_f32_e32 v4, 0x4f7ffffe, v4
	v_cvt_u32_f32_e32 v4, v4
	v_mul_lo_u32 v1, v3, v4
	v_mul_hi_u32 v1, v4, v1
	v_add_u32_e32 v1, v4, v1
	v_mul_hi_u32 v1, v5, v1
	v_mul_lo_u32 v3, v1, v2
	v_sub_u32_e32 v3, v5, v3
	v_add_u32_e32 v4, 1, v1
	v_cmp_ge_u32_e32 vcc, v3, v2
	s_nop 1
	v_cndmask_b32_e32 v1, v1, v4, vcc
	v_sub_u32_e32 v4, v3, v2
	v_cndmask_b32_e32 v3, v3, v4, vcc
	v_add_u32_e32 v4, 1, v1
	v_cmp_ge_u32_e32 vcc, v3, v2
	v_add_u32_e32 v3, 1, v5
	s_nop 0
	v_cndmask_b32_e32 v1, v1, v4, vcc
	v_mul_lo_u32 v4, v2, v1
	v_add_u32_e32 v2, v4, v2
	v_cmp_ne_u32_e32 vcc, v3, v2
	s_and_saveexec_b64 s[6:7], vcc
	s_xor_b64 s[6:7], exec, s[6:7]
	s_cbranch_execz .LBB0_228
	s_waitcnt lgkmcnt(0)
	v_sub_u32_e32 v3, v5, v4
	v_cmp_eq_u32_e32 vcc, 16, v3
	s_cbranch_vccz .Lmidflush_1
	buffer_wbl2 sc1
.Lmidflush_1:
	global_load_dword v0, v185, s[4:5] offset:1280 sc1
	s_add_u32 s10, s4, 0x3500
	s_addc_u32 s11, s5, 0
	s_waitcnt vmcnt(0)
	v_cmp_eq_u32_e32 vcc, v0, v1
	s_and_saveexec_b64 s[8:9], vcc
	s_cbranch_execz .LBB0_227
	s_mov_b32 s19, 1
	s_mov_b64 s[12:13], 0
	s_branch .LBB0_218
